# prompt attention: skip the 16-instruction running-max accumulator init when the running max is zero in every lane (MFMA with C=0)
# speedup vs baseline: 1.0074x; 1.0025x over previous
.LBB0_972:
	s_mul_i32 s1, s52, 0xa000
	s_waitcnt lgkmcnt(0)
	s_barrier
	v_cmp_le_i32_e32 vcc, s0, v165
	s_and_saveexec_b64 s[36:37], vcc
	s_cbranch_execz .Lpa_masked
	v_add_u32_e32 v6, s1, v176
	v_readfirstlane_b32 vcc_lo, v170
	s_add_i32 s1, s1, 0xffff6000
	s_cmp_lg_u32 s52, 0
	s_cselect_b32 s1, s1, 0x14000
	v_add_u32_e32 v14, v6, v172
	ds_read_b128 v[182:185], v14
	ds_read_b128 v[186:189], v14 offset:4096
	v_add_u32_e32 v15, v6, v173
	ds_read_b128 v[190:193], v15
	ds_read_b128 v[194:197], v15 offset:4096
	v_add_u32_e32 v180, v6, v174
	ds_read_b128 v[198:201], v180
	ds_read_b128 v[202:205], v180 offset:4096
	v_add_u32_e32 v181, v6, v175
	ds_read_b128 v[206:209], v181
	ds_read_b128 v[210:213], v181 offset:4096
	s_add_i32 s1, s1, vcc_lo
	v_cmp_ne_u32_e32 vcc, 0, v179
	s_cbranch_vccnz .Lpa_si
	s_waitcnt lgkmcnt(7)
	v_mfma_f32_32x32x16_bf16 v[96:111], v[182:185], v[112:115], 0
	ds_read_b128 v[182:185], v14 offset:8192
	s_waitcnt lgkmcnt(7)
	v_mfma_f32_32x32x16_bf16 v[80:95], v[186:189], v[112:115], 0
	ds_read_b128 v[186:189], v14 offset:12288
	s_branch .Lpa_s2
.Lpa_si:
	s_nop 9
	v_xor_b32_e32 v80, 0x80000000, v179
	v_mov_b32_e32 v81, v80
	v_mov_b32_e32 v82, v80
	v_mov_b32_e32 v83, v80
	v_mov_b32_e32 v84, v80
	v_mov_b32_e32 v85, v80
	v_mov_b32_e32 v86, v80
	v_mov_b32_e32 v87, v80
	v_mov_b32_e32 v88, v80
	v_mov_b32_e32 v89, v80
	v_mov_b32_e32 v90, v80
	v_mov_b32_e32 v91, v80
	v_mov_b32_e32 v92, v80
	v_mov_b32_e32 v93, v80
	v_mov_b32_e32 v94, v80
	v_mov_b32_e32 v95, v80
	s_nop 1
	s_waitcnt lgkmcnt(7)
	v_mfma_f32_32x32x16_bf16 v[96:111], v[182:185], v[112:115], v[80:95]
	ds_read_b128 v[182:185], v14 offset:8192
	s_waitcnt lgkmcnt(7)
	v_mfma_f32_32x32x16_bf16 v[80:95], v[186:189], v[112:115], v[80:95]
	ds_read_b128 v[186:189], v14 offset:12288
.Lpa_s2:
	s_waitcnt lgkmcnt(7)
	v_mfma_f32_32x32x16_bf16 v[96:111], v[190:193], v[116:119], v[96:111]
	ds_read_b128 v[190:193], v15 offset:8192
	s_cmp_ge_i32 s0, s51
	s_cbranch_scc1 .Lpa_nd0
	s_mov_b32 m0, s1
	s_nop 0
	global_load_lds_dwordx4 v0, s[30:31]

.Lpa_nd4:
	s_waitcnt lgkmcnt(7)
	v_mfma_f32_32x32x16_bf16 v[80:95], v[194:197], v[148:151], v[80:95]
	ds_read_b128 v[194:197], v14 offset:36864
	s_waitcnt lgkmcnt(7)
	v_mfma_f32_32x32x16_bf16 v[96:111], v[198:201], v[152:155], v[96:111]
	ds_read_b128 v[198:201], v15 offset:24576
	s_waitcnt lgkmcnt(7)
	v_mfma_f32_32x32x16_bf16 v[80:95], v[202:205], v[152:155], v[80:95]
	ds_read_b128 v[202:205], v15 offset:28672
	s_waitcnt lgkmcnt(7)
	v_mfma_f32_32x32x16_bf16 v[96:111], v[206:209], v[156:159], v[96:111]
	ds_read_b128 v[206:209], v15 offset:32768
	s_waitcnt lgkmcnt(7)
	v_mfma_f32_32x32x16_bf16 v[80:95], v[210:213], v[156:159], v[80:95]
	ds_read_b128 v[210:213], v15 offset:36864
	s_nop 7
	v_max_f32_e32 v2, v96, v97
	v_max3_f32 v2, v2, v98, v99
	v_max3_f32 v2, v2, v100, v101
	v_max3_f32 v2, v2, v102, v103
	v_max3_f32 v2, v2, v104, v105
	v_max3_f32 v2, v2, v106, v107
	v_max3_f32 v2, v2, v108, v109
	v_max3_f32 v2, v2, v110, v111
	v_max_f32_e32 v3, v80, v81
	v_max3_f32 v3, v3, v82, v83
	v_max3_f32 v3, v3, v84, v85
	v_max3_f32 v3, v3, v86, v87
	v_max3_f32 v3, v3, v88, v89
	v_max3_f32 v3, v3, v90, v91
	v_max3_f32 v3, v3, v92, v93
	v_max3_f32 v3, v3, v94, v95
	v_max_f32_e32 v2, v2, v3
	ds_bpermute_b32 v3, v164, v2
	s_waitcnt lgkmcnt(0)
	v_max_f32_e32 v3, v3, v3
	v_max_f32_e32 v2, v2, v3
	v_cmp_lt_f32_e32 vcc, 0x41000000, v2
	s_cbranch_vccz .Lpa_nors
	v_max_f32_e32 v2, v2, v2
	v_max_f32_e32 v2, 0, v2
	v_exp_f32_e64 v4, -v2
	v_add_f32_e32 v179, v179, v2
	v_pk_add_f32 v[96:97], v[96:97], v[2:3] op_sel_hi:[1,0] neg_lo:[0,1] neg_hi:[0,1]
	v_pk_add_f32 v[98:99], v[98:99], v[2:3] op_sel_hi:[1,0] neg_lo:[0,1] neg_hi:[0,1]
	v_pk_add_f32 v[100:101], v[100:101], v[2:3] op_sel_hi:[1,0] neg_lo:[0,1] neg_hi:[0,1]
	v_pk_add_f32 v[102:103], v[102:103], v[2:3] op_sel_hi:[1,0] neg_lo:[0,1] neg_hi:[0,1]
	v_pk_add_f32 v[104:105], v[104:105], v[2:3] op_sel_hi:[1,0] neg_lo:[0,1] neg_hi:[0,1]
	v_pk_add_f32 v[106:107], v[106:107], v[2:3] op_sel_hi:[1,0] neg_lo:[0,1] neg_hi:[0,1]
	v_pk_add_f32 v[108:109], v[108:109], v[2:3] op_sel_hi:[1,0] neg_lo:[0,1] neg_hi:[0,1]
	v_pk_add_f32 v[110:111], v[110:111], v[2:3] op_sel_hi:[1,0] neg_lo:[0,1] neg_hi:[0,1]
	v_pk_add_f32 v[80:81], v[80:81], v[2:3] op_sel_hi:[1,0] neg_lo:[0,1] neg_hi:[0,1]
	v_pk_add_f32 v[82:83], v[82:83], v[2:3] op_sel_hi:[1,0] neg_lo:[0,1] neg_hi:[0,1]
	v_pk_add_f32 v[84:85], v[84:85], v[2:3] op_sel_hi:[1,0] neg_lo:[0,1] neg_hi:[0,1]
	v_pk_add_f32 v[86:87], v[86:87], v[2:3] op_sel_hi:[1,0] neg_lo:[0,1] neg_hi:[0,1]
	v_pk_add_f32 v[88:89], v[88:89], v[2:3] op_sel_hi:[1,0] neg_lo:[0,1] neg_hi:[0,1]
	v_pk_add_f32 v[90:91], v[90:91], v[2:3] op_sel_hi:[1,0] neg_lo:[0,1] neg_hi:[0,1]
	v_pk_add_f32 v[92:93], v[92:93], v[2:3] op_sel_hi:[1,0] neg_lo:[0,1] neg_hi:[0,1]
	v_pk_add_f32 v[94:95], v[94:95], v[2:3] op_sel_hi:[1,0] neg_lo:[0,1] neg_hi:[0,1]
	v_pk_mul_f32 v[78:79], v[78:79], v[4:5] op_sel_hi:[1,0]
	v_pk_mul_f32 v[76:77], v[76:77], v[4:5] op_sel_hi:[1,0]
	v_pk_mul_f32 v[74:75], v[74:75], v[4:5] op_sel_hi:[1,0]
	v_pk_mul_f32 v[72:73], v[72:73], v[4:5] op_sel_hi:[1,0]
	v_pk_mul_f32 v[70:71], v[70:71], v[4:5] op_sel_hi:[1,0]
	v_pk_mul_f32 v[68:69], v[68:69], v[4:5] op_sel_hi:[1,0]
	v_pk_mul_f32 v[66:67], v[66:67], v[4:5] op_sel_hi:[1,0]
	v_pk_mul_f32 v[64:65], v[64:65], v[4:5] op_sel_hi:[1,0]
	v_pk_mul_f32 v[62:63], v[62:63], v[4:5] op_sel_hi:[1,0]
	v_pk_mul_f32 v[60:61], v[60:61], v[4:5] op_sel_hi:[1,0]
	v_pk_mul_f32 v[58:59], v[58:59], v[4:5] op_sel_hi:[1,0]
	v_pk_mul_f32 v[56:57], v[56:57], v[4:5] op_sel_hi:[1,0]
	v_pk_mul_f32 v[54:55], v[54:55], v[4:5] op_sel_hi:[1,0]
	v_pk_mul_f32 v[52:53], v[52:53], v[4:5] op_sel_hi:[1,0]
	v_pk_mul_f32 v[50:51], v[50:51], v[4:5] op_sel_hi:[1,0]
	v_pk_mul_f32 v[48:49], v[48:49], v[4:5] op_sel_hi:[1,0]
	v_pk_mul_f32 v[46:47], v[46:47], v[4:5] op_sel_hi:[1,0]
	v_pk_mul_f32 v[44:45], v[44:45], v[4:5] op_sel_hi:[1,0]
	v_pk_mul_f32 v[42:43], v[42:43], v[4:5] op_sel_hi:[1,0]
	v_pk_mul_f32 v[40:41], v[40:41], v[4:5] op_sel_hi:[1,0]
	v_pk_mul_f32 v[38:39], v[38:39], v[4:5] op_sel_hi:[1,0]
	v_pk_mul_f32 v[36:37], v[36:37], v[4:5] op_sel_hi:[1,0]
	v_pk_mul_f32 v[34:35], v[34:35], v[4:5] op_sel_hi:[1,0]
	v_pk_mul_f32 v[32:33], v[32:33], v[4:5] op_sel_hi:[1,0]
	v_pk_mul_f32 v[30:31], v[30:31], v[4:5] op_sel_hi:[1,0]
	v_pk_mul_f32 v[28:29], v[28:29], v[4:5] op_sel_hi:[1,0]
	v_pk_mul_f32 v[26:27], v[26:27], v[4:5] op_sel_hi:[1,0]
	v_pk_mul_f32 v[24:25], v[24:25], v[4:5] op_sel_hi:[1,0]
	v_pk_mul_f32 v[22:23], v[22:23], v[4:5] op_sel_hi:[1,0]
	v_pk_mul_f32 v[20:21], v[20:21], v[4:5] op_sel_hi:[1,0]
	v_pk_mul_f32 v[18:19], v[18:19], v[4:5] op_sel_hi:[1,0]
	v_pk_mul_f32 v[16:17], v[16:17], v[4:5] op_sel_hi:[1,0]
	v_mul_f32_e32 v171, v171, v4
.Lpa_nors:
	v_exp_f32_e32 v96, v96
	v_exp_f32_e32 v97, v97
	v_exp_f32_e32 v98, v98
	v_exp_f32_e32 v99, v99
	v_add_f32_e32 v2, 0, v96
	v_exp_f32_e32 v100, v100
	v_add_f32_e32 v2, v97, v2
	v_exp_f32_e32 v101, v101
	v_add_f32_e32 v2, v98, v2
	v_exp_f32_e32 v102, v102
	v_add_f32_e32 v2, v99, v2
	v_exp_f32_e32 v103, v103
	v_add_f32_e32 v2, v100, v2
	v_exp_f32_e32 v104, v104
	v_add_f32_e32 v2, v101, v2
	v_exp_f32_e32 v105, v105
	v_add_f32_e32 v2, v102, v2
	v_exp_f32_e32 v106, v106
	v_add_f32_e32 v2, v103, v2
	v_cvt_pk_bf16_f32 v214, v96, v97
	v_cvt_pk_bf16_f32 v215, v98, v99
	v_cvt_pk_bf16_f32 v216, v100, v101
	v_cvt_pk_bf16_f32 v217, v102, v103
	v_exp_f32_e32 v107, v107
	v_add_f32_e32 v2, v104, v2
	v_exp_f32_e32 v108, v108
	v_add_f32_e32 v2, v105, v2
	v_exp_f32_e32 v109, v109
	v_add_f32_e32 v2, v106, v2
	v_exp_f32_e32 v110, v110
	v_add_f32_e32 v2, v107, v2
	v_exp_f32_e32 v111, v111
	v_add_f32_e32 v2, v108, v2
	v_exp_f32_e32 v80, v80
	v_add_f32_e32 v2, v109, v2
	v_exp_f32_e32 v81, v81
	v_add_f32_e32 v2, v110, v2
	v_exp_f32_e32 v82, v82
	v_add_f32_e32 v2, v111, v2
	v_cvt_pk_bf16_f32 v218, v104, v105
	v_cvt_pk_bf16_f32 v219, v106, v107
	v_cvt_pk_bf16_f32 v220, v108, v109
	v_cvt_pk_bf16_f32 v221, v110, v111
	v_exp_f32_e32 v83, v83
	v_add_f32_e32 v2, v80, v2
	v_exp_f32_e32 v84, v84
	v_add_f32_e32 v2, v81, v2
	v_exp_f32_e32 v85, v85
	v_add_f32_e32 v2, v82, v2
	v_exp_f32_e32 v86, v86
	v_add_f32_e32 v2, v83, v2
	v_exp_f32_e32 v87, v87
	v_add_f32_e32 v2, v84, v2
	v_exp_f32_e32 v88, v88
	v_add_f32_e32 v2, v85, v2
	v_exp_f32_e32 v89, v89
	v_add_f32_e32 v2, v86, v2
	v_exp_f32_e32 v90, v90
	v_add_f32_e32 v2, v87, v2
	v_cvt_pk_bf16_f32 v222, v80, v81
	v_cvt_pk_bf16_f32 v223, v82, v83
	v_cvt_pk_bf16_f32 v224, v84, v85
	v_cvt_pk_bf16_f32 v225, v86, v87
	v_exp_f32_e32 v91, v91
	v_add_f32_e32 v2, v88, v2
	v_exp_f32_e32 v92, v92
	v_add_f32_e32 v2, v89, v2
	v_exp_f32_e32 v93, v93
	v_add_f32_e32 v2, v90, v2
	v_exp_f32_e32 v94, v94
	v_add_f32_e32 v2, v91, v2
	v_exp_f32_e32 v95, v95
	v_add_f32_e32 v2, v92, v2
	v_add_f32_e32 v2, v93, v2
	v_add_f32_e32 v2, v94, v2
	v_add_f32_e32 v2, v95, v2
	v_cvt_pk_bf16_f32 v226, v88, v89
	v_cvt_pk_bf16_f32 v227, v90, v91
	v_cvt_pk_bf16_f32 v228, v92, v93
	v_cvt_pk_bf16_f32 v229, v94, v95
	v_add_f32_e32 v171, v171, v2
	s_waitcnt lgkmcnt(8)
	v_mfma_f32_32x32x16_bf16 v[64:79], v[182:185], v[214:217], v[64:79]
	ds_read_b128 v[182:185], v180 offset:24576
	s_waitcnt lgkmcnt(8)
	v_mfma_f32_32x32x16_bf16 v[48:63], v[186:189], v[214:217], v[48:63]
	ds_read_b128 v[186:189], v180 offset:28672
	s_waitcnt lgkmcnt(8)
	v_mfma_f32_32x32x16_bf16 v[32:47], v[190:193], v[214:217], v[32:47]
	ds_read_b128 v[190:193], v180 offset:32768
	s_waitcnt lgkmcnt(8)
	v_mfma_f32_32x32x16_bf16 v[16:31], v[194:197], v[214:217], v[16:31]
	ds_read_b128 v[194:197], v180 offset:36864
	s_waitcnt lgkmcnt(8)
	v_mfma_f32_32x32x16_bf16 v[64:79], v[198:201], v[218:221], v[64:79]
	ds_read_b128 v[198:201], v181 offset:24576
	s_waitcnt lgkmcnt(8)
	v_mfma_f32_32x32x16_bf16 v[48:63], v[202:205], v[218:221], v[48:63]
	ds_read_b128 v[202:205], v181 offset:28672
	s_waitcnt lgkmcnt(8)
	v_mfma_f32_32x32x16_bf16 v[32:47], v[206:209], v[218:221], v[32:47]
	ds_read_b128 v[206:209], v181 offset:32768
	s_waitcnt lgkmcnt(8)
	v_mfma_f32_32x32x16_bf16 v[16:31], v[210:213], v[218:221], v[16:31]
	ds_read_b128 v[210:213], v181 offset:36864
	s_waitcnt lgkmcnt(7)
	v_mfma_f32_32x32x16_bf16 v[64:79], v[182:185], v[222:225], v[64:79]
	s_waitcnt lgkmcnt(6)
	v_mfma_f32_32x32x16_bf16 v[48:63], v[186:189], v[222:225], v[48:63]
	s_waitcnt lgkmcnt(5)
	v_mfma_f32_32x32x16_bf16 v[32:47], v[190:193], v[222:225], v[32:47]
	s_waitcnt lgkmcnt(4)
	v_mfma_f32_32x32x16_bf16 v[16:31], v[194:197], v[222:225], v[16:31]
	s_waitcnt lgkmcnt(3)
	v_mfma_f32_32x32x16_bf16 v[64:79], v[198:201], v[226:229], v[64:79]
	s_waitcnt lgkmcnt(2)
	v_mfma_f32_32x32x16_bf16 v[48:63], v[202:205], v[226:229], v[48:63]
	s_waitcnt lgkmcnt(1)
	v_mfma_f32_32x32x16_bf16 v[32:47], v[206:209], v[226:229], v[32:47]
	s_waitcnt lgkmcnt(0)
	v_mfma_f32_32x32x16_bf16 v[16:31], v[210:213], v[226:229], v[16:31]
	s_nop 0
